# scan chunk stages A/O/S: LDS fragment reads hoisted into dead registers, counted lgkmcnt waits, MFMAs back to back; x^T fragments read once per chunk in stage S
# speedup vs baseline: 1.0605x; 1.0172x over previous
; __device__ __forceinline__ f32x4 mfma16(bf16x8 a, bf16x8 b, f32x4 c) { return __builtin_amdgcn_mfma_f32_16x16x32_bf16(a, b, c, 0, 0, 0); }
; __device__ __forceinline__ void st4(u16* dst, float a, float b, float c, float d) { uint2 v; v.x = pack2(a, b); v.y = pack2(c, d); *(uint2*)dst = v; }
; __device__ void scan_unit_mma(const Params& p, int l, int g, int u, CSmem& sm) {
;     ...
;       int si, ti; bool doit = true;
;       si = w & 1; ti = w >> 1; doit = !(si == 1 && ti == 0);
;       if (doit) {
;         f32x4 acc = f32x4{0.f, 0.f, 0.f, 0.f};
; #pragma unroll
;         for (int kk = 0; kk < 4; ++kk)
;           acc = mfma16(ldf(&sm.KA[0][0], 136, si * 16 + fr, kk * 32 + fq * 8), ldf(&sm.QA[0][0], 136, ti * 16 + fr, kk * 32 + fq * 8), acc);
;         const int t = ti * 16 + fr;
;         float o4[4];
;         if (mixer == 0) {
; #pragma unroll
;           for (int j = 0; j < 4; ++j) { int s_ = si * 16 + fq * 4 + j; o4[j] = (s_ <= t) ? acc[j] : 0.f; }
;         } else if (mixer == 1) {
;           float Gt = sm.sc[t][0];
; #pragma unroll
;           for (int j = 0; j < 4; ++j) { int s_ = si * 16 + fq * 4 + j; o4[j] = (s_ <= t) ? acc[j] * __expf(Gt - sm.sc[s_][0]) : 0.f; }
;         } else {
;           float Mt = sm.sc[t][2];
; #pragma unroll
;           for (int j = 0; j < 4; ++j) { int s_ = si * 16 + fq * 4 + j; o4[j] = (s_ <= t) ? acc[j] * QS * __expf(sm.sc[s_][1] - Mt) : 0.f; }
;         }
;         st4(&sm.ATT[t][si * 16 + fq * 4], o4[0], o4[1], o4[2], o4[3]);
;       } else {
;         int t = lane >> 2, s4 = (lane & 3) * 4; *(uint2*)&sm.ATT[t][16 + s4] = uint2{0u, 0u};
.LBB0_670:
	v_and_b32_e32 v73, 15, v109
	v_lshrrev_b32_e32 v66, 4, v113
	v_and_b32_e32 v65, 1, v3
	s_andn2_b64 vcc, exec, s[56:57]
	v_ashrrev_i32_e32 v64, 7, v109
	s_cbranch_vccnz .LBB0_688
	v_cmp_ne_u32_e32 vcc, 0, v65
	v_cmp_gt_u32_e64 s[40:41], s33, v109
	s_and_b64 s[40:41], s[40:41], vcc
	s_and_saveexec_b64 s[42:43], s[40:41]
	s_xor_b64 s[40:41], exec, s[42:43]
	v_lshrrev_b32_e32 v0, 2, v113
	v_and_b32_e32 v2, 24, v2
	v_mad_u32_u24 v0, v0, s5, v2
	ds_write_b64 v0, v[198:199] offset:32800
	s_andn2_saveexec_b64 s[40:41], s[40:41]
	s_cbranch_execz .LBB0_687
	v_lshlrev_b32_e32 v67, 4, v65
	v_or_b32_e32 v60, v67, v73
	v_lshlrev_b32_e32 v68, 4, v66
	v_mad_u32_u24 v69, v60, s27, v68
	v_lshl_or_b32 v2, v64, 4, v73
	v_mul_lo_u32 v0, v2, s27
	v_add_u32_e32 v68, v0, v68
	ds_read_b128 v[200:203], v69 offset:8704
	ds_read_b128 v[204:207], v68
	ds_read_b128 v[208:211], v69 offset:8768
	ds_read_b128 v[212:215], v68 offset:64
	ds_read_b128 v[216:219], v69 offset:8832
	ds_read_b128 v[220:223], v68 offset:128
	ds_read_b128 v[224:227], v69 offset:8896
	ds_read_b128 v[228:231], v68 offset:192
	s_mov_b64 s[42:43], -1
	s_and_b64 vcc, exec, s[46:47]
	s_waitcnt lgkmcnt(6)
	v_mfma_f32_16x16x32_bf16 v[60:63], v[200:203], v[204:207], 0
	s_waitcnt lgkmcnt(4)
	v_mfma_f32_16x16x32_bf16 v[60:63], v[208:211], v[212:215], v[60:63]
	s_waitcnt lgkmcnt(2)
	v_mfma_f32_16x16x32_bf16 v[60:63], v[216:219], v[220:223], v[60:63]
	s_waitcnt lgkmcnt(0)
	v_mfma_f32_16x16x32_bf16 v[60:63], v[224:227], v[228:231], v[60:63]
	s_cbranch_vccz .LBB0_684
	s_movk_i32 s42, 0xff10
	v_mad_u64_u32 v[68:69], s[42:43], v2, s42, v[0:1]
	ds_read_b32 v74, v68 offset:52744
	v_lshl_or_b32 v76, v66, 2, v67
	v_cmp_le_i32_e32 vcc, v76, v2
	v_mov_b32_e32 v69, 0
	v_lshlrev_b32_e32 v75, 5, v76
	v_mov_b32_e32 v68, 0
	s_and_saveexec_b64 s[42:43], vcc
	s_cbranch_execz .LBB0_677
	ds_read_b32 v68, v75 offset:52740
	v_mul_f32_e32 v70, 0x3db504f3, v60
	s_waitcnt lgkmcnt(0)
	v_sub_f32_e32 v68, v68, v74
	v_mul_f32_e32 v68, 0x3fb8aa3b, v68
	v_exp_f32_e32 v68, v68
	s_nop 0
	v_mul_f32_e32 v68, v70, v68

; __device__ __forceinline__ f32x4 mfma16(bf16x8 a, bf16x8 b, f32x4 c) { return __builtin_amdgcn_mfma_f32_16x16x32_bf16(a, b, c, 0, 0, 0); }
; __device__ void scan_unit_mma(const Params& p, int l, int g, int u, CSmem& sm) {
;     ...
;     {
;       f32x4 acc[2];
;       acc[0] = acc[1] = f32x4{0.f, 0.f, 0.f, 0.f};
;       const u16* Qs = (mixer == 0) ? &sm.u.hg.QD[0][0] : &sm.QA[0][0];
; #pragma unroll
;       for (int kk = 0; kk < 4; ++kk) {
;         bf16x8 qb = ldf(Qs, 136, rt_o * 16 + fr, kk * 32 + fq * 8);
; #pragma unroll
;         for (int c = 0; c < 2; ++c) acc[c] = mfma16(ldf(&sm.ST[0][0], 136, (cp_o * 2 + c) * 16 + fr, kk * 32 + fq * 8), qb, acc[c]);
;       }
;       const int t = rt_o * 16 + fr;
;       float rs, fs;
;       if (mixer == 0) { rs = 1.f; fs = 1.f; }
;       else if (mixer == 1) { rs = __expf(sm.sc[t][0]); fs = 1.f; }
;       else { rs = QS * __expf(mcar - sm.sc[t][2]); fs = sm.sc[t][4]; }
; #pragma unroll
;       for (int c = 0; c < 2; ++c)
; #pragma unroll
;         for (int j = 0; j < 4; ++j) acc[c][j] *= rs;
;       {
;         bf16x8 ab = ldf(&sm.ATT[0][0], 40, rt_o * 16 + fr, fq * 8);
; #pragma unroll
;         for (int c = 0; c < 2; ++c) acc[c] = mfma16(ldf(&sm.XT[0][0], 40, (cp_o * 2 + c) * 16 + fr, fq * 8), ab, acc[c]);
;       }
.LBB0_698:
	v_lshlrev_b32_e32 v68, 5, v64
	v_or_b32_e32 v75, v68, v73
	v_mad_u64_u32 v[84:85], s[40:41], v75, s27, v[2:3]
	v_mul_u32_u24_e32 v60, 0x110, v74
	v_add3_u32 v70, s73, v60, v2
	ds_read_b128 v[200:203], v70
	ds_read_b128 v[216:219], v84 offset:35328
	ds_read_b128 v[232:235], v84 offset:39680
	ds_read_b128 v[204:207], v70 offset:64
	ds_read_b128 v[220:223], v84 offset:35392
	ds_read_b128 v[236:239], v84 offset:39744
	ds_read_b128 v[208:211], v70 offset:128
	ds_read_b128 v[224:227], v84 offset:35456
	ds_read_b128 v[244:247], v84 offset:39808
	ds_read_b128 v[212:215], v70 offset:192
	ds_read_b128 v[228:231], v84 offset:35520
	ds_read_b128 v[248:251], v84 offset:39872
	v_mov_b32_e32 v72, 1.0
	s_andn2_b64 vcc, exec, s[46:47]
	s_waitcnt lgkmcnt(9)
	v_mfma_f32_16x16x32_bf16 v[60:63], v[216:219], v[200:203], 0
	v_mfma_f32_16x16x32_bf16 v[64:67], v[232:235], v[200:203], 0
	s_waitcnt lgkmcnt(6)
	v_mfma_f32_16x16x32_bf16 v[60:63], v[220:223], v[204:207], v[60:63]
	v_mfma_f32_16x16x32_bf16 v[64:67], v[236:239], v[204:207], v[64:67]
	s_waitcnt lgkmcnt(3)
	v_mfma_f32_16x16x32_bf16 v[60:63], v[224:227], v[208:211], v[60:63]
	v_mfma_f32_16x16x32_bf16 v[64:67], v[244:247], v[208:211], v[64:67]
	s_waitcnt lgkmcnt(0)
	v_mfma_f32_16x16x32_bf16 v[60:63], v[228:231], v[212:215], v[60:63]
	v_mfma_f32_16x16x32_bf16 v[64:67], v[248:251], v[212:215], v[64:67]
	v_mov_b32_e32 v70, 1.0
	s_cbranch_vccnz .LBB0_703
	s_nop 1
	v_lshlrev_b32_e32 v76, 5, v74
	s_mov_b64 s[40:41], -1
	s_and_b64 vcc, exec, s[56:57]
	s_cbranch_vccz .LBB0_701
	v_add_u32_e32 v70, 0xcc00, v76
	ds_read2_b32 v[78:79], v70 offset0:130 offset1:132
	s_mov_b64 s[40:41], 0
	s_waitcnt lgkmcnt(0)
	v_sub_f32_e32 v70, v108, v78
	v_mul_f32_e32 v70, 0x3fb8aa3b, v70
	v_exp_f32_e32 v70, v70
	s_nop 0
	v_mul_f32_e32 v72, 0x3db504f3, v70
	v_mov_b32_e32 v70, v79

; __device__ __forceinline__ float bf2f(u16 h) { return __uint_as_float(((unsigned)h) << 16); }
; __device__ __forceinline__ f32x4 mfma16(bf16x8 a, bf16x8 b, f32x4 c) { return __builtin_amdgcn_mfma_f32_16x16x32_bf16(a, b, c, 0, 0, 0); }
; __device__ __forceinline__ void st4(u16* dst, float a, float b, float c, float d) { uint2 v; v.x = pack2(a, b); v.y = pack2(c, d); *(uint2*)dst = v; }
; __device__ void scan_unit_mma(const Params& p, int l, int g, int u, CSmem& sm) {
;     ...
;     {
;       float dsc = 1.f;
;       if (mixer == 1) dsc = __expf(sm.sc[31][0]);
;       else if (mixer == 2) dsc = __expf(mcar - sm.sc[31][2]);
; #pragma unroll
;       for (int rt = 0; rt < 2; ++rt) {
;         if (mixer == 0) {
;           float4 d4 = *(const float4*)&sm.u.hg.dec[w * 32 + rt * 16 + fq * 4];
; #pragma unroll
;           for (int ct = 0; ct < 4; ++ct) { S[rt][ct][0] *= d4.x; S[rt][ct][1] *= d4.y; S[rt][ct][2] *= d4.z; S[rt][ct][3] *= d4.w; }
;         } else {
; #pragma unroll
;           for (int ct = 0; ct < 4; ++ct) { S[rt][ct][0] *= dsc; S[rt][ct][1] *= dsc; S[rt][ct][2] *= dsc; S[rt][ct][3] *= dsc; }
;         }
;         bf16x8 a = ldf(&sm.KDT[0][0], 40, w * 32 + rt * 16 + fr, fq * 8);
; #pragma unroll
;         for (int ct = 0; ct < 4; ++ct) {
;           S[rt][ct] = mfma16(a, ldf(&sm.XT[0][0], 40, ct * 16 + fr, fq * 8), S[rt][ct]);
;           st4(&sm.ST[ct * 16 + fr][w * 32 + rt * 16 + fq * 4], S[rt][ct][0], S[rt][ct][1], S[rt][ct][2], S[rt][ct][3]);
;         }
;       }
;       if (mixer == 2) {
;         if (tid < 128) {
;           float sum = 0.f;
; #pragma unroll
;           for (int e = 0; e < 32; ++e) sum += bf2f(sm.KDT[tid][e]);
;           sm.u.ml.nvec[tid] = dsc * sm.u.ml.nvec[tid] + sum;
;         }
.LBB0_711:
	v_lshlrev_b32_e32 v65, 5, v3
	s_waitcnt lgkmcnt(0)
	v_pk_mul_f32 v[28:29], v[28:29], v[60:61]
	v_pk_mul_f32 v[36:37], v[36:37], v[60:61]
	v_pk_mul_f32 v[44:45], v[44:45], v[60:61]
	v_pk_mul_f32 v[52:53], v[52:53], v[60:61]
	v_or_b32_e32 v60, v65, v73
	v_mad_u64_u32 v[60:61], s[68:69], v60, s5, v[2:3]
	v_pk_mul_f32 v[30:31], v[30:31], v[62:63]
	v_pk_mul_f32 v[38:39], v[38:39], v[62:63]
	v_pk_mul_f32 v[46:47], v[46:47], v[62:63]
	v_pk_mul_f32 v[54:55], v[54:55], v[62:63]
	ds_read_b128 v[60:63], v60 offset:17408
	v_mad_u32_u24 v67, v73, s5, v2
	ds_read_b128 v[200:203], v67 offset:27648
	ds_read_b128 v[204:207], v67 offset:28928
	ds_read_b128 v[208:211], v67 offset:30208
	ds_read_b128 v[212:215], v67 offset:31488
	v_sub_u32_e32 v0, v2, v0
	v_lshlrev_b32_e32 v3, 6, v3
	v_mul_u32_u24_e32 v68, 0x110, v73
	v_add3_u32 v0, v0, v3, v68
	s_and_b64 vcc, exec, s[42:43]
	s_waitcnt lgkmcnt(3)
	v_mfma_f32_16x16x32_bf16 v[28:31], v[60:63], v[200:203], v[28:31]
	s_waitcnt lgkmcnt(2)
	v_mfma_f32_16x16x32_bf16 v[36:39], v[60:63], v[204:207], v[36:39]
	s_waitcnt lgkmcnt(1)
	v_mfma_f32_16x16x32_bf16 v[44:47], v[60:63], v[208:211], v[44:47]
	s_waitcnt lgkmcnt(0)
	v_mfma_f32_16x16x32_bf16 v[52:55], v[60:63], v[212:215], v[52:55]
	s_nop 7
	v_cvt_pk_bf16_f32 v216, v28, v29
	v_cvt_pk_bf16_f32 v217, v30, v31
	ds_write_b64 v0, v[216:217] offset:35328
	v_cvt_pk_bf16_f32 v218, v36, v37
	v_cvt_pk_bf16_f32 v219, v38, v39
	ds_write_b64 v0, v[218:219] offset:39680
	v_cvt_pk_bf16_f32 v220, v44, v45
	v_cvt_pk_bf16_f32 v221, v46, v47
	ds_write_b64 v0, v[220:221] offset:44032
	v_cvt_pk_bf16_f32 v222, v52, v53
	v_cvt_pk_bf16_f32 v223, v54, v55
	ds_write_b64 v0, v[222:223] offset:48384
	v_mov_b64_e32 v[62:63], v[64:65]
	v_mov_b32_e32 v63, v64
	v_mov_b64_e32 v[60:61], v[64:65]
	v_mov_b32_e32 v61, v64
	s_cbranch_vccnz .LBB0_713
	ds_read_b128 v[60:63], v66 offset:62528
.LBB0_713:
	v_mul_u32_u24_e32 v3, 0x50, v73
	s_waitcnt lgkmcnt(0)
	v_pk_mul_f32 v[32:33], v[32:33], v[60:61]
	v_pk_mul_f32 v[40:41], v[40:41], v[60:61]
	v_pk_mul_f32 v[48:49], v[48:49], v[60:61]
	v_pk_mul_f32 v[56:57], v[56:57], v[60:61]
	v_or3_b32 v60, v65, v73, 16
	v_mad_u64_u32 v[60:61], s[42:43], v60, s5, v[2:3]
	v_pk_mul_f32 v[34:35], v[34:35], v[62:63]
	v_pk_mul_f32 v[42:43], v[42:43], v[62:63]
	v_pk_mul_f32 v[50:51], v[50:51], v[62:63]
	v_pk_mul_f32 v[58:59], v[58:59], v[62:63]
	ds_read_b128 v[60:63], v60 offset:17408
	s_and_b64 vcc, exec, s[40:41]
	s_waitcnt lgkmcnt(0)
	v_mfma_f32_16x16x32_bf16 v[32:35], v[60:63], v[200:203], v[32:35]
	v_mfma_f32_16x16x32_bf16 v[40:43], v[60:63], v[204:207], v[40:43]
	v_mfma_f32_16x16x32_bf16 v[48:51], v[60:63], v[208:211], v[48:51]
	v_mfma_f32_16x16x32_bf16 v[56:59], v[60:63], v[212:215], v[56:59]
	s_nop 7
	v_cvt_pk_bf16_f32 v216, v32, v33
	v_cvt_pk_bf16_f32 v217, v34, v35
	ds_write_b64 v0, v[216:217] offset:35360
	v_cvt_pk_bf16_f32 v218, v40, v41
	v_cvt_pk_bf16_f32 v219, v42, v43
	ds_write_b64 v0, v[218:219] offset:39712
	v_cvt_pk_bf16_f32 v220, v48, v49
	v_cvt_pk_bf16_f32 v221, v50, v51
	ds_write_b64 v0, v[220:221] offset:44064
	v_cvt_pk_bf16_f32 v222, v56, v57
	v_cvt_pk_bf16_f32 v223, v58, v59
	ds_write_b64 v0, v[222:223] offset:48416
	s_cbranch_vccnz .LBB0_638
	v_cmp_gt_i32_e32 vcc, s33, v109
	s_and_saveexec_b64 s[40:41], vcc
	s_cbranch_execz .LBB0_637
	v_mul_lo_u32 v0, v109, s5
	ds_read_b128 v[60:63], v0 offset:17408
	ds_read_b128 v[66:69], v0 offset:17424
	ds_read_b128 v[72:75], v0 offset:17440
	ds_read_b128 v[76:79], v0 offset:17456
	s_waitcnt lgkmcnt(3)
	v_lshlrev_b32_e32 v0, 16, v60
	v_and_b32_e32 v2, 0xffff0000, v60
	v_add_f32_e32 v0, 0, v0
	v_add_f32_e32 v0, v0, v2
	v_lshlrev_b32_e32 v2, 16, v61
	v_add_f32_e32 v0, v0, v2
	v_and_b32_e32 v2, 0xffff0000, v61
	v_add_f32_e32 v0, v0, v2
	v_lshlrev_b32_e32 v2, 16, v62
	v_add_f32_e32 v0, v0, v2
	v_and_b32_e32 v2, 0xffff0000, v62
	v_add_f32_e32 v0, v0, v2
	v_lshlrev_b32_e32 v2, 16, v63
	v_add_f32_e32 v0, v0, v2
	v_and_b32_e32 v2, 0xffff0000, v63
	v_add_f32_e32 v0, v0, v2
	s_waitcnt lgkmcnt(2)
	v_lshlrev_b32_e32 v2, 16, v66
	v_add_f32_e32 v0, v0, v2
	v_and_b32_e32 v2, 0xffff0000, v66
	v_add_f32_e32 v0, v0, v2
	v_lshlrev_b32_e32 v2, 16, v67
	v_add_f32_e32 v0, v0, v2
	v_and_b32_e32 v2, 0xffff0000, v67
	v_add_f32_e32 v0, v0, v2
	v_lshlrev_b32_e32 v2, 16, v68
	v_add_f32_e32 v0, v0, v2
	v_and_b32_e32 v2, 0xffff0000, v68
	v_add_f32_e32 v0, v0, v2
	v_lshlrev_b32_e32 v2, 16, v69
	v_add_f32_e32 v0, v0, v2
	v_and_b32_e32 v2, 0xffff0000, v69
	v_add_f32_e32 v0, v0, v2
	s_waitcnt lgkmcnt(1)
	v_lshlrev_b32_e32 v2, 16, v72
	v_add_f32_e32 v0, v0, v2
	v_and_b32_e32 v2, 0xffff0000, v72
	v_add_f32_e32 v0, v0, v2
	v_lshlrev_b32_e32 v2, 16, v73
	v_add_f32_e32 v0, v0, v2
	v_and_b32_e32 v2, 0xffff0000, v73
	v_add_f32_e32 v0, v0, v2
	v_lshlrev_b32_e32 v2, 16, v74
	v_add_f32_e32 v0, v0, v2
	v_and_b32_e32 v2, 0xffff0000, v74
	v_add_f32_e32 v0, v0, v2
	v_lshlrev_b32_e32 v2, 16, v75
	v_add_f32_e32 v0, v0, v2
	v_and_b32_e32 v2, 0xffff0000, v75
	v_add_f32_e32 v0, v0, v2
	s_waitcnt lgkmcnt(0)
	v_lshlrev_b32_e32 v2, 16, v76
	v_add_f32_e32 v0, v0, v2
	v_and_b32_e32 v2, 0xffff0000, v76
	v_add_f32_e32 v0, v0, v2
	v_lshlrev_b32_e32 v2, 16, v77
	v_add_f32_e32 v0, v0, v2
	v_and_b32_e32 v2, 0xffff0000, v77
	v_add_f32_e32 v0, v0, v2
	v_lshlrev_b32_e32 v2, 16, v78
	v_add_f32_e32 v0, v0, v2
	v_and_b32_e32 v2, 0xffff0000, v78
	v_add_f32_e32 v0, v0, v2
	v_lshlrev_b32_e32 v2, 2, v109
	ds_read_b32 v3, v2 offset:53760
	v_lshlrev_b32_e32 v60, 16, v79
	v_add_f32_e32 v0, v0, v60
	v_and_b32_e32 v60, 0xffff0000, v79
	v_add_f32_e32 v0, v0, v60
	s_waitcnt lgkmcnt(0)
	v_fmac_f32_e32 v0, v64, v3
	ds_write_b32 v2, v0 offset:53760
	s_branch .LBB0_637
